# plus barrier leader releases followers before its own invalidate; phase-12 queue hands out chunk units first
# baseline (speedup 1.0000x reference)
.LBB0_210:
	s_xor_b32 s38, s38, 0x400
	v_mov_b32_e32 v184, 0
	s_and_saveexec_b64 s[4:5], s[42:43]
	s_cbranch_execz .LBB0_214
	s_mov_b64 s[8:9], exec
	v_mbcnt_lo_u32_b32 v0, s8, 0
	v_mbcnt_hi_u32_b32 v0, s9, v0
	v_cmp_eq_u32_e32 vcc, 0, v0
	s_and_saveexec_b64 s[6:7], vcc
	s_cbranch_execz .LBB0_213
	s_bcnt1_i32_b64 s8, s[8:9]
	v_mov_b32_e32 v1, s8
	v_readlane_b32 s8, v255, 59
	v_readlane_b32 s9, v255, 60
	s_nop 4
	global_atomic_add v1, v193, v1, s[8:9] offset:4 sc0

.LBB0_537:
	s_or_b64 exec, exec, s[6:7]
	s_mov_b64 s[6:7], exec
	v_mbcnt_lo_u32_b32 v0, s6, 0
	v_mbcnt_hi_u32_b32 v0, s7, v0
	v_cmp_eq_u32_e32 vcc, 0, v0
	s_waitcnt vmcnt(0)
	s_and_saveexec_b64 s[8:9], vcc
	s_cbranch_execz .LBB0_539
	s_bcnt1_i32_b64 s6, s[6:7]
	v_mov_b32_e32 v0, s6
	v_readlane_b32 s6, v253, 8
	v_readlane_b32 s7, v253, 9
	s_nop 4
	global_atomic_add v193, v0, s[6:7]
.LBB0_539:
	s_or_b64 exec, exec, s[8:9]
	buffer_inv sc1
	s_waitcnt vmcnt(0)
